# K-loop LDS-DMA rebalance: SB(0,1) pair moved from phase B to phase C in FFN-up and W_in loops (2/4/4/6), phase-B wait vmcnt 8->6
# speedup vs baseline: 1.0020x; 1.0020x over previous
;     __device__ bool next(int i, Unit& u) const { const bool ok = StaticOrder::next(i / 3, u); u.seg = i % 3; return ok; }
; #define PG8_STAGE(bufoff, gbase, voff) do { _Pragma("unroll") for (int _i = 0; _i < 2; ++_i) \
;         __builtin_amdgcn_global_load_lds((const unsigned*)((const char*)(gbase) + (voff)[_i]), (LAS unsigned*)(lds + (bufoff) + ldsw + _i * 8192), 16, 0, PG8_AUX); } while (0)
; #define PG8_LDA(dst, b, h) do { _Pragma("unroll") for (int m = 0; m < 4; ++m) _Pragma("unroll") for (int k = 0; k < 2; ++k) dst[m][k] = *(const LAS bf16x8*)(lds + PG8_SA(b, h) + aoff + m * 2048 + k * 1024); } while (0)
; #define PG8_LDB(dst, b, h) do { _Pragma("unroll") for (int n = 0; n < 2; ++n) _Pragma("unroll") for (int k = 0; k < 2; ++k) dst[n][k] = *(const LAS bf16x8*)(lds + PG8_SB(b, h) + boff + n * 2048 + k * 1024); } while (0)
; #define PG8_WAIT_V(n) asm volatile("s_waitcnt vmcnt(" #n ")" ::: "memory")
; #define PG8_WAIT_L(n) asm volatile("s_waitcnt lgkmcnt(" #n ")" ::: "memory")
; #define PG8_BAR __builtin_amdgcn_s_barrier()
; template <class Epi, class Sched>
; __device__ __forceinline__ void gemm_phase(LAS unsigned char* lds, const Gemm g, const Sched& S, const Epi& E) {
;     ...
;         const bool has_next = S.next(ui + 1, nxt);
;         const char* nA = has_next ? (const char*)g.A + (size_t)(g.fix ? 0 : nxt.pm) * tstepA + (size_t)S.koff(nxt) * 2 : cA; const char* nB = has_next ? (const char*)g.Bt + (size_t)(g.fix ? 0 : nxt.pn) * tstepB + (size_t)S.koff(nxt) * 2 : cB;
;         for (int t = 0; t < nt; t += 2) {
;             const bool last = (t == nt - 2);
;             const char* a1 = cA + (size_t)(t + 1) * kstep;
;             const char* a2 = last ? nA : cA + (size_t)(t + 2) * kstep; const char* b2 = last ? nB : cB + (size_t)(t + 2) * kstep;
;             const char* a3 = a2 + kstep; const char* b3 = b2 + kstep;
;     ...
;             PG8_LDB(B0, 0, 0); PG8_LDB(B1, 0, 1); PG8_SCHED; PG8_LDA(At, 0, 0); PG8_STAGE(PG8_SA(1, 1), a1 + hstepA, voffA);
;             PG8_WAIT_V(8); PG8_WAIT_L(0); PG8_BAR; PG8_MMA(0, 0, At, B0); PG8_MMA(0, 1, At, B1); PG8_BAR; PG8_SCHED;
;             PG8_LDA(At, 0, 1); PG8_STAGE(PG8_SB(0, 0), b2, voffB); PG8_STAGE(PG8_SB(0, 1), b2 + hstepB, voffB); PG8_STAGE(PG8_SA(0, 0), a2, voffA);
;             PG8_WAIT_V(8); PG8_WAIT_L(0); PG8_BAR; PG8_MMA(1, 0, At, B0); PG8_MMA(1, 1, At, B1); PG8_BAR; PG8_SCHED;
.LBB0_382:
	s_add_u32 s4, s0, 0xfff80080
	s_addc_u32 s22, s1, -1
	s_add_i32 s78, 0, 0x10000
	s_cmp_eq_u32 s65, 28
	s_cselect_b32 s41, s20, s22
	s_cselect_b32 s40, s27, s4
	v_add_u32_e32 v136, s78, v182
	s_cselect_b32 s23, s49, s64
	s_cselect_b32 s22, s51, s63
	s_add_i32 s4, 0, 0x14000
	ds_read_b128 v[160:163], v136
	ds_read_b128 v[164:167], v136 offset:1024
	ds_read_b128 v[168:171], v136 offset:2048
	ds_read_b128 v[186:189], v136 offset:3072
	v_add_u32_e32 v136, s4, v182
	ds_read_b128 v[194:197], v136
	ds_read_b128 v[198:201], v136 offset:1024
	ds_read_b128 v[202:205], v136 offset:2048
	ds_read_b128 v[206:209], v136 offset:3072
	v_lshl_add_u64 v[172:173], s[0:1], 0, v[156:157]
	s_add_i32 m0, s30, 0xc000
	ds_read_b128 v[210:213], v184
	ds_read_b128 v[214:217], v184 offset:1024
	ds_read_b128 v[218:221], v184 offset:2048
	ds_read_b128 v[222:225], v184 offset:3072
	ds_read_b128 v[226:229], v184 offset:4096
	ds_read_b128 v[230:233], v184 offset:5120
	ds_read_b128 v[234:237], v184 offset:6144
	ds_read_b128 v[238:241], v184 offset:7168
	global_load_lds_dwordx4 v[172:173], off
	v_lshl_add_u64 v[172:173], s[0:1], 0, v[158:159]
	s_add_i32 m0, s30, 0xe000
	s_nop 0
	global_load_lds_dwordx4 v[172:173], off
	s_waitcnt vmcnt(8)
	s_waitcnt lgkmcnt(0)
	s_barrier
	s_setprio 1
	s_waitcnt lgkmcnt(0)
	v_mfma_f32_16x16x32_bf16 v[124:127], v[160:163], v[210:213], v[124:127]
	v_mfma_f32_16x16x32_bf16 v[120:123], v[168:171], v[210:213], v[120:123]
	v_mfma_f32_16x16x32_bf16 v[108:111], v[160:163], v[218:221], v[108:111]
	v_mfma_f32_16x16x32_bf16 v[104:107], v[168:171], v[218:221], v[104:107]
	v_mfma_f32_16x16x32_bf16 v[92:95], v[160:163], v[226:229], v[92:95]
	v_mfma_f32_16x16x32_bf16 v[88:91], v[168:171], v[226:229], v[88:91]
	v_mfma_f32_16x16x32_bf16 v[76:79], v[160:163], v[234:237], v[76:79]
	v_mfma_f32_16x16x32_bf16 v[72:75], v[168:171], v[234:237], v[72:75]
	v_mfma_f32_16x16x32_bf16 v[124:127], v[164:167], v[214:217], v[124:127]
	v_mfma_f32_16x16x32_bf16 v[120:123], v[186:189], v[214:217], v[120:123]
	v_mfma_f32_16x16x32_bf16 v[108:111], v[164:167], v[222:225], v[108:111]
	v_mfma_f32_16x16x32_bf16 v[104:107], v[186:189], v[222:225], v[104:107]
	v_mfma_f32_16x16x32_bf16 v[92:95], v[164:167], v[230:233], v[92:95]
	v_mfma_f32_16x16x32_bf16 v[88:91], v[186:189], v[230:233], v[88:91]
	v_mfma_f32_16x16x32_bf16 v[76:79], v[164:167], v[238:241], v[76:79]
	v_mfma_f32_16x16x32_bf16 v[72:75], v[186:189], v[238:241], v[72:75]
	s_setprio 0
	s_setprio 1
	v_mfma_f32_16x16x32_bf16 v[116:119], v[194:197], v[210:213], v[116:119]
	v_mfma_f32_16x16x32_bf16 v[112:115], v[202:205], v[210:213], v[112:115]
	v_mfma_f32_16x16x32_bf16 v[100:103], v[194:197], v[218:221], v[100:103]
	v_mfma_f32_16x16x32_bf16 v[96:99], v[202:205], v[218:221], v[96:99]
	v_mfma_f32_16x16x32_bf16 v[84:87], v[194:197], v[226:229], v[84:87]
	v_mfma_f32_16x16x32_bf16 v[80:83], v[202:205], v[226:229], v[80:83]
	v_mfma_f32_16x16x32_bf16 v[68:71], v[194:197], v[234:237], v[68:71]
	v_mfma_f32_16x16x32_bf16 v[64:67], v[202:205], v[234:237], v[64:67]
	v_mfma_f32_16x16x32_bf16 v[116:119], v[198:201], v[214:217], v[116:119]
	v_mfma_f32_16x16x32_bf16 v[112:115], v[206:209], v[214:217], v[112:115]
	v_mfma_f32_16x16x32_bf16 v[100:103], v[198:201], v[222:225], v[100:103]
	v_mfma_f32_16x16x32_bf16 v[96:99], v[206:209], v[222:225], v[96:99]
	v_mfma_f32_16x16x32_bf16 v[84:87], v[198:201], v[230:233], v[84:87]
	v_mfma_f32_16x16x32_bf16 v[80:83], v[206:209], v[230:233], v[80:83]
	v_mfma_f32_16x16x32_bf16 v[68:71], v[198:201], v[238:241], v[68:71]
	v_mfma_f32_16x16x32_bf16 v[64:67], v[206:209], v[238:241], v[64:67]
	s_setprio 0
	s_barrier
	s_add_i32 s78, s78, s28
	v_lshl_add_u64 v[172:173], s[22:23], 0, v[132:133]
	s_mov_b32 m0, s78
	ds_read_b128 v[210:213], v184 offset:16384
	ds_read_b128 v[214:217], v184 offset:17408
	ds_read_b128 v[218:221], v184 offset:18432
	ds_read_b128 v[222:225], v184 offset:19456
	ds_read_b128 v[226:229], v184 offset:20480
	ds_read_b128 v[230:233], v184 offset:21504
	ds_read_b128 v[234:237], v184 offset:22528
	ds_read_b128 v[238:241], v184 offset:23552
	global_load_lds_dwordx4 v[172:173], off
	s_add_i32 m0, s78, 0x2000
	s_add_u32 vcc_lo, s22, 0x80000
	v_lshl_add_u64 v[190:191], s[22:23], 0, v[128:129]
	s_addc_u32 vcc_hi, s23, 0
	s_add_i32 s4, s4, s28
	global_load_lds_dwordx4 v[190:191], off
	v_lshl_add_u64 v[244:245], s[40:41], 0, v[130:131]
	v_lshl_add_u64 v[242:243], s[40:41], 0, v[134:135]
	s_mov_b32 m0, s30
	s_nop 0
	global_load_lds_dwordx4 v[242:243], off
	s_mov_b32 m0, s34
	s_nop 0
	global_load_lds_dwordx4 v[244:245], off
	s_waitcnt vmcnt(6)
	s_waitcnt lgkmcnt(0)
	s_barrier
; #define PG8_STAGE(bufoff, gbase, voff) do { _Pragma("unroll") for (int _i = 0; _i < 2; ++_i) \
;         __builtin_amdgcn_global_load_lds((const unsigned*)((const char*)(gbase) + (voff)[_i]), (LAS unsigned*)(lds + (bufoff) + ldsw + _i * 8192), 16, 0, PG8_AUX); } while (0)
; #define PG8_LDA(dst, b, h) do { _Pragma("unroll") for (int m = 0; m < 4; ++m) _Pragma("unroll") for (int k = 0; k < 2; ++k) dst[m][k] = *(const LAS bf16x8*)(lds + PG8_SA(b, h) + aoff + m * 2048 + k * 1024); } while (0)
; #define PG8_LDB(dst, b, h) do { _Pragma("unroll") for (int n = 0; n < 2; ++n) _Pragma("unroll") for (int k = 0; k < 2; ++k) dst[n][k] = *(const LAS bf16x8*)(lds + PG8_SB(b, h) + boff + n * 2048 + k * 1024); } while (0)
; #define PG8_MMA(ai, bj, At, Bt) do { __builtin_amdgcn_s_setprio(1); _Pragma("unroll") for (int m = 0; m < 4; ++m) _Pragma("unroll") for (int n = 0; n < 2; ++n) _Pragma("unroll") for (int k = 0; k < 2; ++k) \
;         acc[ai][bj][m][n] = __builtin_amdgcn_mfma_f32_16x16x32_bf16(Bt[n][k], At[m][k], acc[ai][bj][m][n], 0, 0, 0); __builtin_amdgcn_s_setprio(0); } while (0)
; #define PG8_WAIT_V(n) asm volatile("s_waitcnt vmcnt(" #n ")" ::: "memory")
; #define PG8_WAIT_L(n) asm volatile("s_waitcnt lgkmcnt(" #n ")" ::: "memory")
; #define PG8_BAR __builtin_amdgcn_s_barrier()
; #define PG8_SCHED __builtin_amdgcn_sched_barrier(0)
; template <class Epi, class Sched>
; __device__ __forceinline__ void gemm_phase(LAS unsigned char* lds, const Gemm g, const Sched& S, const Epi& E) {
;     ...
;             PG8_WAIT_V(8); PG8_WAIT_L(0); PG8_BAR; PG8_MMA(1, 0, At, B0); PG8_MMA(1, 1, At, B1); PG8_BAR; PG8_SCHED;
;             PG8_LDB(B0, 1, 0); PG8_LDB(B1, 1, 1); PG8_SCHED; PG8_LDA(At, 1, 0); PG8_STAGE(PG8_SA(0, 1), a2 + hstepA, voffA);
;             PG8_WAIT_V(8); PG8_WAIT_L(0); PG8_BAR; PG8_MMA(0, 0, At, B0); PG8_MMA(0, 1, At, B1); PG8_BAR; PG8_SCHED;
	s_setprio 1
	s_waitcnt lgkmcnt(0)
	v_mfma_f32_16x16x32_bf16 v[60:63], v[160:163], v[210:213], v[60:63]
	v_mfma_f32_16x16x32_bf16 v[56:59], v[168:171], v[210:213], v[56:59]
	v_mfma_f32_16x16x32_bf16 v[44:47], v[160:163], v[218:221], v[44:47]
	v_mfma_f32_16x16x32_bf16 v[40:43], v[168:171], v[218:221], v[40:43]
	v_mfma_f32_16x16x32_bf16 v[28:31], v[160:163], v[226:229], v[28:31]
	v_mfma_f32_16x16x32_bf16 v[24:27], v[168:171], v[226:229], v[24:27]
	v_mfma_f32_16x16x32_bf16 v[12:15], v[160:163], v[234:237], v[12:15]
	v_mfma_f32_16x16x32_bf16 v[8:11], v[168:171], v[234:237], v[8:11]
	v_mfma_f32_16x16x32_bf16 v[60:63], v[164:167], v[214:217], v[60:63]
	v_mfma_f32_16x16x32_bf16 v[56:59], v[186:189], v[214:217], v[56:59]
	v_mfma_f32_16x16x32_bf16 v[44:47], v[164:167], v[222:225], v[44:47]
	v_mfma_f32_16x16x32_bf16 v[40:43], v[186:189], v[222:225], v[40:43]
	v_mfma_f32_16x16x32_bf16 v[28:31], v[164:167], v[230:233], v[28:31]
	v_mfma_f32_16x16x32_bf16 v[24:27], v[186:189], v[230:233], v[24:27]
	v_mfma_f32_16x16x32_bf16 v[12:15], v[164:167], v[238:241], v[12:15]
	v_mfma_f32_16x16x32_bf16 v[8:11], v[186:189], v[238:241], v[8:11]
	s_setprio 0
	s_setprio 1
	v_mfma_f32_16x16x32_bf16 v[52:55], v[194:197], v[210:213], v[52:55]
	v_mfma_f32_16x16x32_bf16 v[48:51], v[202:205], v[210:213], v[48:51]
	v_mfma_f32_16x16x32_bf16 v[36:39], v[194:197], v[218:221], v[36:39]
	v_mfma_f32_16x16x32_bf16 v[32:35], v[202:205], v[218:221], v[32:35]
	v_mfma_f32_16x16x32_bf16 v[20:23], v[194:197], v[226:229], v[20:23]
	v_mfma_f32_16x16x32_bf16 v[16:19], v[202:205], v[226:229], v[16:19]
	v_mfma_f32_16x16x32_bf16 v[4:7], v[194:197], v[234:237], v[4:7]
	v_mfma_f32_16x16x32_bf16 v[0:3], v[202:205], v[234:237], v[0:3]
	v_mfma_f32_16x16x32_bf16 v[52:55], v[198:201], v[214:217], v[52:55]
	v_mfma_f32_16x16x32_bf16 v[48:51], v[206:209], v[214:217], v[48:51]
	v_mfma_f32_16x16x32_bf16 v[36:39], v[198:201], v[222:225], v[36:39]
	v_mfma_f32_16x16x32_bf16 v[32:35], v[206:209], v[222:225], v[32:35]
	v_mfma_f32_16x16x32_bf16 v[20:23], v[198:201], v[230:233], v[20:23]
	v_mfma_f32_16x16x32_bf16 v[16:19], v[206:209], v[230:233], v[16:19]
	v_mfma_f32_16x16x32_bf16 v[4:7], v[198:201], v[238:241], v[4:7]
	v_mfma_f32_16x16x32_bf16 v[0:3], v[206:209], v[238:241], v[0:3]
	s_setprio 0
	s_barrier
	s_add_i32 s4, 0, 0x18000
	v_add_u32_e32 v136, s4, v182
	s_add_i32 s78, 0, 0x1c000
	ds_read_b128 v[160:163], v136
	ds_read_b128 v[164:167], v136 offset:1024
	ds_read_b128 v[168:171], v136 offset:2048
	ds_read_b128 v[186:189], v136 offset:3072
	v_add_u32_e32 v136, s78, v182
	ds_read_b128 v[194:197], v136
	ds_read_b128 v[198:201], v136 offset:1024
	ds_read_b128 v[202:205], v136 offset:2048
	ds_read_b128 v[206:209], v136 offset:3072
	s_add_u32 s40, s40, 0x80000
	s_addc_u32 s41, s41, 0
	s_mov_b32 m0, s36
	v_lshl_add_u64 v[246:247], s[40:41], 0, v[134:135]
	ds_read_b128 v[210:213], v184 offset:32768
	ds_read_b128 v[214:217], v184 offset:33792
	ds_read_b128 v[218:221], v184 offset:34816
	ds_read_b128 v[222:225], v184 offset:35840
	ds_read_b128 v[226:229], v184 offset:36864
	ds_read_b128 v[230:233], v184 offset:37888
	ds_read_b128 v[234:237], v184 offset:38912
	ds_read_b128 v[238:241], v184 offset:39936
	s_add_u32 s100, s22, 0x80000
	s_addc_u32 s101, s23, 0
	s_add_i32 m0, s28, 0x14000
	s_nop 0
	global_load_lds_dwordx4 v132, s[100:101]
	s_add_i32 m0, s28, 0x16000
	s_nop 0
	global_load_lds_dwordx4 v128, s[100:101]
	s_mov_b32 m0, s36
	s_nop 0
	global_load_lds_dwordx4 v[246:247], off
	v_lshl_add_u64 v[246:247], s[40:41], 0, v[130:131]
	s_mov_b32 m0, s60
	s_nop 0
	global_load_lds_dwordx4 v[246:247], off
	s_waitcnt vmcnt(8)
	s_waitcnt lgkmcnt(0)
	s_barrier
	s_setprio 1
	s_waitcnt lgkmcnt(0)
	v_mfma_f32_16x16x32_bf16 v[124:127], v[160:163], v[210:213], v[124:127]
	v_mfma_f32_16x16x32_bf16 v[120:123], v[168:171], v[210:213], v[120:123]
	v_mfma_f32_16x16x32_bf16 v[108:111], v[160:163], v[218:221], v[108:111]
	v_mfma_f32_16x16x32_bf16 v[104:107], v[168:171], v[218:221], v[104:107]
	v_mfma_f32_16x16x32_bf16 v[92:95], v[160:163], v[226:229], v[92:95]
	v_mfma_f32_16x16x32_bf16 v[88:91], v[168:171], v[226:229], v[88:91]
	v_mfma_f32_16x16x32_bf16 v[76:79], v[160:163], v[234:237], v[76:79]
	v_mfma_f32_16x16x32_bf16 v[72:75], v[168:171], v[234:237], v[72:75]
	v_mfma_f32_16x16x32_bf16 v[124:127], v[164:167], v[214:217], v[124:127]
	v_mfma_f32_16x16x32_bf16 v[120:123], v[186:189], v[214:217], v[120:123]
	v_mfma_f32_16x16x32_bf16 v[108:111], v[164:167], v[222:225], v[108:111]
	v_mfma_f32_16x16x32_bf16 v[104:107], v[186:189], v[222:225], v[104:107]
	v_mfma_f32_16x16x32_bf16 v[92:95], v[164:167], v[230:233], v[92:95]
	v_mfma_f32_16x16x32_bf16 v[88:91], v[186:189], v[230:233], v[88:91]
	v_mfma_f32_16x16x32_bf16 v[76:79], v[164:167], v[238:241], v[76:79]
	v_mfma_f32_16x16x32_bf16 v[72:75], v[186:189], v[238:241], v[72:75]
	s_setprio 0
	s_setprio 1
	v_mfma_f32_16x16x32_bf16 v[116:119], v[194:197], v[210:213], v[116:119]
	v_mfma_f32_16x16x32_bf16 v[112:115], v[202:205], v[210:213], v[112:115]
	v_mfma_f32_16x16x32_bf16 v[100:103], v[194:197], v[218:221], v[100:103]
	v_mfma_f32_16x16x32_bf16 v[96:99], v[202:205], v[218:221], v[96:99]
	v_mfma_f32_16x16x32_bf16 v[84:87], v[194:197], v[226:229], v[84:87]
	v_mfma_f32_16x16x32_bf16 v[80:83], v[202:205], v[226:229], v[80:83]
	v_mfma_f32_16x16x32_bf16 v[68:71], v[194:197], v[234:237], v[68:71]
	v_mfma_f32_16x16x32_bf16 v[64:67], v[202:205], v[234:237], v[64:67]
	v_mfma_f32_16x16x32_bf16 v[116:119], v[198:201], v[214:217], v[116:119]
	v_mfma_f32_16x16x32_bf16 v[112:115], v[206:209], v[214:217], v[112:115]
	v_mfma_f32_16x16x32_bf16 v[100:103], v[198:201], v[222:225], v[100:103]
	v_mfma_f32_16x16x32_bf16 v[96:99], v[206:209], v[222:225], v[96:99]
	v_mfma_f32_16x16x32_bf16 v[84:87], v[198:201], v[230:233], v[84:87]
	v_mfma_f32_16x16x32_bf16 v[80:83], v[206:209], v[230:233], v[80:83]
	v_mfma_f32_16x16x32_bf16 v[68:71], v[198:201], v[238:241], v[68:71]
	v_mfma_f32_16x16x32_bf16 v[64:67], v[206:209], v[238:241], v[64:67]
	s_setprio 0
	s_barrier
; #define PG8_STAGE(bufoff, gbase, voff) do { _Pragma("unroll") for (int _i = 0; _i < 2; ++_i) \
;         __builtin_amdgcn_global_load_lds((const unsigned*)((const char*)(gbase) + (voff)[_i]), (LAS unsigned*)(lds + (bufoff) + ldsw + _i * 8192), 16, 0, PG8_AUX); } while (0)
; #define PG8_LDA(dst, b, h) do { _Pragma("unroll") for (int m = 0; m < 4; ++m) _Pragma("unroll") for (int k = 0; k < 2; ++k) dst[m][k] = *(const LAS bf16x8*)(lds + PG8_SA(b, h) + aoff + m * 2048 + k * 1024); } while (0)
; #define PG8_WAIT_V(n) asm volatile("s_waitcnt vmcnt(" #n ")" ::: "memory")
; #define PG8_WAIT_L(n) asm volatile("s_waitcnt lgkmcnt(" #n ")" ::: "memory")
; template <class Epi, class Sched>
; __device__ __forceinline__ void gemm_phase(LAS unsigned char* lds, const Gemm g, const Sched& S, const Epi& E) {
;     ...
;             PG8_LDA(At, 1, 1); PG8_STAGE(PG8_SB(1, 0), b3, voffB); PG8_STAGE(PG8_SB(1, 1), b3 + hstepB, voffB); PG8_STAGE(PG8_SA(1, 0), a3, voffA);
;             PG8_WAIT_V(8); PG8_WAIT_L(0); PG8_BAR; PG8_MMA(1, 0, At, B0); PG8_MMA(1, 1, At, B1); PG8_BAR; PG8_SCHED;
;     ...
;             PG8_LDB(B0, 0, 0); PG8_SCHED; PG8_LDA(At, 0, 0); PG8_STAGE(PG8_SA(1, 1), a1 + hstepA, voffA);
;             PG8_WAIT_L(8); PG8_BAR; PG8_WAIT_L(0); PG8_MMA(0, 0, At, B0); PG8_BAR; PG8_SCHED;
;             PG8_LDB(B1, 0, 1); PG8_STAGE(PG8_SB(0, 0), b2, voffB);
;             PG8_BAR; PG8_WAIT_L(0); PG8_MMA(0, 1, At, B1); PG8_BAR;
;             PG8_LDA(At, 0, 1); PG8_STAGE(PG8_SA(0, 0), a2, voffA);
;             PG8_BAR; PG8_WAIT_L(0); PG8_MMA(1, 0, At, B0); PG8_BAR; PG8_SCHED;
;             PG8_STAGE(PG8_SB(0, 1), b2 + hstepB, voffB);
;             PG8_WAIT_V(6); PG8_BAR; PG8_MMA(1, 1, At, B1); PG8_BAR;
;             PG8_LDB(B0, 1, 0); PG8_SCHED; PG8_LDA(At, 1, 0); PG8_STAGE(PG8_SA(0, 1), a2 + hstepA, voffA);
;             PG8_WAIT_L(8); PG8_BAR; PG8_WAIT_L(0); PG8_MMA(0, 0, At, B0); PG8_BAR; PG8_SCHED;
;             PG8_LDB(B1, 1, 1); PG8_STAGE(PG8_SB(1, 0), b3, voffB);
;             PG8_BAR; PG8_WAIT_L(0); PG8_MMA(0, 1, At, B1); PG8_BAR;
;             PG8_LDA(At, 1, 1); PG8_STAGE(PG8_SA(1, 0), a3, voffA);
;             PG8_BAR; PG8_WAIT_L(0); PG8_MMA(1, 0, At, B0); PG8_BAR; PG8_SCHED;
;             PG8_STAGE(PG8_SB(1, 1), b3 + hstepB, voffB);
;             PG8_WAIT_V(6); PG8_BAR; PG8_MMA(1, 1, At, B1); PG8_BAR;
;     ...
;         }
;     ...
;         if (wr == 0) PG8_BAR;
	s_add_i32 s4, s4, s28
	v_lshl_add_u64 v[172:173], v[172:173], 0, s[12:13]
	s_mov_b32 m0, s4
	ds_read_b128 v[210:213], v184 offset:49152
	ds_read_b128 v[214:217], v184 offset:50176
	ds_read_b128 v[218:221], v184 offset:51200
	ds_read_b128 v[222:225], v184 offset:52224
	ds_read_b128 v[226:229], v184 offset:53248
	ds_read_b128 v[230:233], v184 offset:54272
	ds_read_b128 v[234:237], v184 offset:55296
	ds_read_b128 v[238:241], v184 offset:56320
	global_load_lds_dwordx4 v[172:173], off
	s_add_i32 m0, s4, 0x2000
	s_add_u32 s22, s22, 0x80080
	v_lshl_add_u64 v[172:173], v[190:191], 0, s[12:13]
	s_addc_u32 s23, s23, 0
	s_add_i32 s4, s78, s28
	global_load_lds_dwordx4 v[172:173], off
	v_lshl_add_u64 v[172:173], s[22:23], 0, v[132:133]
	s_mov_b32 m0, s4
	s_nop 0
	global_load_lds_dwordx4 v[172:173], off
	v_lshl_add_u64 v[172:173], s[22:23], 0, v[128:129]
	s_add_i32 m0, s4, 0x2000
	s_nop 0
	global_load_lds_dwordx4 v[172:173], off
	v_lshl_add_u64 v[172:173], v[242:243], 0, s[12:13]
	s_mov_b32 m0, s61
	s_nop 0
	global_load_lds_dwordx4 v[172:173], off
	v_lshl_add_u64 v[172:173], v[244:245], 0, s[12:13]
	s_mov_b32 m0, s62
	s_nop 0
	global_load_lds_dwordx4 v[172:173], off
	s_waitcnt vmcnt(8)
	s_waitcnt lgkmcnt(0)
	s_barrier
	s_setprio 1
	s_waitcnt lgkmcnt(0)
	v_mfma_f32_16x16x32_bf16 v[60:63], v[160:163], v[210:213], v[60:63]
	v_mfma_f32_16x16x32_bf16 v[56:59], v[168:171], v[210:213], v[56:59]
	v_mfma_f32_16x16x32_bf16 v[44:47], v[160:163], v[218:221], v[44:47]
	v_mfma_f32_16x16x32_bf16 v[40:43], v[168:171], v[218:221], v[40:43]
	v_mfma_f32_16x16x32_bf16 v[28:31], v[160:163], v[226:229], v[28:31]
	v_mfma_f32_16x16x32_bf16 v[24:27], v[168:171], v[226:229], v[24:27]
	v_mfma_f32_16x16x32_bf16 v[12:15], v[160:163], v[234:237], v[12:15]
	v_mfma_f32_16x16x32_bf16 v[8:11], v[168:171], v[234:237], v[8:11]
	v_mfma_f32_16x16x32_bf16 v[60:63], v[164:167], v[214:217], v[60:63]
	v_mfma_f32_16x16x32_bf16 v[56:59], v[186:189], v[214:217], v[56:59]
	v_mfma_f32_16x16x32_bf16 v[44:47], v[164:167], v[222:225], v[44:47]
	v_mfma_f32_16x16x32_bf16 v[40:43], v[186:189], v[222:225], v[40:43]
	v_mfma_f32_16x16x32_bf16 v[28:31], v[164:167], v[230:233], v[28:31]
	v_mfma_f32_16x16x32_bf16 v[24:27], v[186:189], v[230:233], v[24:27]
	v_mfma_f32_16x16x32_bf16 v[12:15], v[164:167], v[238:241], v[12:15]
	v_mfma_f32_16x16x32_bf16 v[8:11], v[186:189], v[238:241], v[8:11]
	s_setprio 0
	s_setprio 1
	v_mfma_f32_16x16x32_bf16 v[52:55], v[194:197], v[210:213], v[52:55]
	v_mfma_f32_16x16x32_bf16 v[48:51], v[202:205], v[210:213], v[48:51]
	v_mfma_f32_16x16x32_bf16 v[36:39], v[194:197], v[218:221], v[36:39]
	v_mfma_f32_16x16x32_bf16 v[32:35], v[202:205], v[218:221], v[32:35]
	v_mfma_f32_16x16x32_bf16 v[20:23], v[194:197], v[226:229], v[20:23]
	v_mfma_f32_16x16x32_bf16 v[16:19], v[202:205], v[226:229], v[16:19]
	v_mfma_f32_16x16x32_bf16 v[4:7], v[194:197], v[234:237], v[4:7]
	v_mfma_f32_16x16x32_bf16 v[0:3], v[202:205], v[234:237], v[0:3]
	v_mfma_f32_16x16x32_bf16 v[52:55], v[198:201], v[214:217], v[52:55]
	v_mfma_f32_16x16x32_bf16 v[48:51], v[206:209], v[214:217], v[48:51]
	v_mfma_f32_16x16x32_bf16 v[36:39], v[198:201], v[222:225], v[36:39]
	v_mfma_f32_16x16x32_bf16 v[32:35], v[206:209], v[222:225], v[32:35]
	v_mfma_f32_16x16x32_bf16 v[20:23], v[198:201], v[230:233], v[20:23]
	v_mfma_f32_16x16x32_bf16 v[16:19], v[206:209], v[230:233], v[16:19]
	v_mfma_f32_16x16x32_bf16 v[4:7], v[198:201], v[238:241], v[4:7]
	v_mfma_f32_16x16x32_bf16 v[0:3], v[206:209], v[238:241], v[0:3]
	s_setprio 0
	s_barrier
	s_add_i32 s65, s65, 2
	s_add_u32 s0, s0, 0x100
	s_addc_u32 s1, s1, 0
	s_add_u32 s63, s63, 0x100
	s_addc_u32 s64, s64, 0
	s_cmp_gt_u32 s65, 29
	s_cbranch_scc0 .LBB0_382
	s_and_b64 vcc, exec, s[46:47]
	s_cbranch_vccz .LBB0_385
	s_barrier

;     __device__ bool next(int i, Unit& u) const { const bool ok = StaticOrder::next(i / 3, u); u.seg = i % 3; return ok; }
; #define PG8_STAGE(bufoff, gbase, voff) do { _Pragma("unroll") for (int _i = 0; _i < 2; ++_i) \
;         __builtin_amdgcn_global_load_lds((const unsigned*)((const char*)(gbase) + (voff)[_i]), (LAS unsigned*)(lds + (bufoff) + ldsw + _i * 8192), 16, 0, PG8_AUX); } while (0)
; #define PG8_LDA(dst, b, h) do { _Pragma("unroll") for (int m = 0; m < 4; ++m) _Pragma("unroll") for (int k = 0; k < 2; ++k) dst[m][k] = *(const LAS bf16x8*)(lds + PG8_SA(b, h) + aoff + m * 2048 + k * 1024); } while (0)
; #define PG8_LDB(dst, b, h) do { _Pragma("unroll") for (int n = 0; n < 2; ++n) _Pragma("unroll") for (int k = 0; k < 2; ++k) dst[n][k] = *(const LAS bf16x8*)(lds + PG8_SB(b, h) + boff + n * 2048 + k * 1024); } while (0)
; #define PG8_WAIT_V(n) asm volatile("s_waitcnt vmcnt(" #n ")" ::: "memory")
; #define PG8_WAIT_L(n) asm volatile("s_waitcnt lgkmcnt(" #n ")" ::: "memory")
; #define PG8_BAR __builtin_amdgcn_s_barrier()
; template <class Epi, class Sched>
; __device__ __forceinline__ void gemm_phase(LAS unsigned char* lds, const Gemm g, const Sched& S, const Epi& E) {
;     ...
;         const bool has_next = S.next(ui + 1, nxt);
;         const char* nA = has_next ? (const char*)g.A + (size_t)(g.fix ? 0 : nxt.pm) * tstepA + (size_t)S.koff(nxt) * 2 : cA; const char* nB = has_next ? (const char*)g.Bt + (size_t)(g.fix ? 0 : nxt.pn) * tstepB + (size_t)S.koff(nxt) * 2 : cB;
;         for (int t = 0; t < nt; t += 2) {
;             const bool last = (t == nt - 2);
;             const char* a1 = cA + (size_t)(t + 1) * kstep;
;             const char* a2 = last ? nA : cA + (size_t)(t + 2) * kstep; const char* b2 = last ? nB : cB + (size_t)(t + 2) * kstep;
;             const char* a3 = a2 + kstep; const char* b3 = b2 + kstep;
;     ...
;             PG8_LDB(B0, 0, 0); PG8_LDB(B1, 0, 1); PG8_SCHED; PG8_LDA(At, 0, 0); PG8_STAGE(PG8_SA(1, 1), a1 + hstepA, voffA);
;             PG8_WAIT_V(8); PG8_WAIT_L(0); PG8_BAR; PG8_MMA(0, 0, At, B0); PG8_MMA(0, 1, At, B1); PG8_BAR; PG8_SCHED;
;             PG8_LDA(At, 0, 1); PG8_STAGE(PG8_SB(0, 0), b2, voffB); PG8_STAGE(PG8_SB(0, 1), b2 + hstepB, voffB); PG8_STAGE(PG8_SA(0, 0), a2, voffA);
;             PG8_WAIT_V(8); PG8_WAIT_L(0); PG8_BAR; PG8_MMA(1, 0, At, B0); PG8_MMA(1, 1, At, B1); PG8_BAR; PG8_SCHED;
.LBB0_745:
	s_add_u32 s4, s22, 0xfff80080
	s_addc_u32 s52, s23, -1
	s_add_i32 s78, 0, 0x10000
	s_cmp_eq_u32 s94, 28
	s_cselect_b32 s55, s45, s52
	s_cselect_b32 s54, s60, s4
	v_add_u32_e32 v160, s78, v163
	s_cselect_b32 s53, s47, s92
	s_cselect_b32 s52, s61, s65
	s_add_i32 s4, 0, 0x14000
	ds_read_b128 v[156:159], v160
	ds_read_b128 v[166:169], v160 offset:1024
	ds_read_b128 v[170:173], v160 offset:2048
	ds_read_b128 v[182:185], v160 offset:3072
	v_add_u32_e32 v160, s4, v163
	ds_read_b128 v[186:189], v160
	ds_read_b128 v[194:197], v160 offset:1024
	ds_read_b128 v[198:201], v160 offset:2048
	ds_read_b128 v[202:205], v160 offset:3072
	v_lshl_add_u64 v[160:161], s[22:23], 0, v[134:135]
	s_add_i32 m0, s36, 0xc000
	ds_read_b128 v[206:209], v165
	ds_read_b128 v[210:213], v165 offset:1024
	ds_read_b128 v[214:217], v165 offset:2048
	ds_read_b128 v[218:221], v165 offset:3072
	ds_read_b128 v[222:225], v165 offset:4096
	ds_read_b128 v[226:229], v165 offset:5120
	ds_read_b128 v[230:233], v165 offset:6144
	ds_read_b128 v[234:237], v165 offset:7168
	global_load_lds_dwordx4 v[160:161], off
	v_lshl_add_u64 v[160:161], s[22:23], 0, v[154:155]
	s_add_i32 m0, s36, 0xe000
	s_nop 0
	global_load_lds_dwordx4 v[160:161], off
	s_waitcnt vmcnt(8)
	s_waitcnt lgkmcnt(0)
	s_barrier
	s_setprio 1
	s_waitcnt lgkmcnt(0)
	v_mfma_f32_16x16x32_bf16 v[124:127], v[156:159], v[206:209], v[124:127]
	v_mfma_f32_16x16x32_bf16 v[116:119], v[170:173], v[206:209], v[116:119]
	v_mfma_f32_16x16x32_bf16 v[108:111], v[156:159], v[214:217], v[108:111]
	v_mfma_f32_16x16x32_bf16 v[100:103], v[170:173], v[214:217], v[100:103]
	v_mfma_f32_16x16x32_bf16 v[92:95], v[156:159], v[222:225], v[92:95]
	v_mfma_f32_16x16x32_bf16 v[84:87], v[170:173], v[222:225], v[84:87]
	v_mfma_f32_16x16x32_bf16 v[76:79], v[156:159], v[230:233], v[76:79]
	v_mfma_f32_16x16x32_bf16 v[68:71], v[170:173], v[230:233], v[68:71]
	v_mfma_f32_16x16x32_bf16 v[124:127], v[166:169], v[210:213], v[124:127]
	v_mfma_f32_16x16x32_bf16 v[116:119], v[182:185], v[210:213], v[116:119]
	v_mfma_f32_16x16x32_bf16 v[108:111], v[166:169], v[218:221], v[108:111]
	v_mfma_f32_16x16x32_bf16 v[100:103], v[182:185], v[218:221], v[100:103]
	v_mfma_f32_16x16x32_bf16 v[92:95], v[166:169], v[226:229], v[92:95]
	v_mfma_f32_16x16x32_bf16 v[84:87], v[182:185], v[226:229], v[84:87]
	v_mfma_f32_16x16x32_bf16 v[76:79], v[166:169], v[234:237], v[76:79]
	v_mfma_f32_16x16x32_bf16 v[68:71], v[182:185], v[234:237], v[68:71]
	s_setprio 0
	s_setprio 1
	v_mfma_f32_16x16x32_bf16 v[120:123], v[186:189], v[206:209], v[120:123]
	v_mfma_f32_16x16x32_bf16 v[112:115], v[198:201], v[206:209], v[112:115]
	v_mfma_f32_16x16x32_bf16 v[104:107], v[186:189], v[214:217], v[104:107]
	v_mfma_f32_16x16x32_bf16 v[96:99], v[198:201], v[214:217], v[96:99]
	v_mfma_f32_16x16x32_bf16 v[88:91], v[186:189], v[222:225], v[88:91]
	v_mfma_f32_16x16x32_bf16 v[80:83], v[198:201], v[222:225], v[80:83]
	v_mfma_f32_16x16x32_bf16 v[72:75], v[186:189], v[230:233], v[72:75]
	v_mfma_f32_16x16x32_bf16 v[64:67], v[198:201], v[230:233], v[64:67]
	v_mfma_f32_16x16x32_bf16 v[120:123], v[194:197], v[210:213], v[120:123]
	v_mfma_f32_16x16x32_bf16 v[112:115], v[202:205], v[210:213], v[112:115]
	v_mfma_f32_16x16x32_bf16 v[104:107], v[194:197], v[218:221], v[104:107]
	v_mfma_f32_16x16x32_bf16 v[96:99], v[202:205], v[218:221], v[96:99]
	v_mfma_f32_16x16x32_bf16 v[88:91], v[194:197], v[226:229], v[88:91]
	v_mfma_f32_16x16x32_bf16 v[80:83], v[202:205], v[226:229], v[80:83]
	v_mfma_f32_16x16x32_bf16 v[72:75], v[194:197], v[234:237], v[72:75]
	v_mfma_f32_16x16x32_bf16 v[64:67], v[202:205], v[234:237], v[64:67]
	s_setprio 0
	s_barrier
	s_add_i32 s78, s78, s34
	v_lshl_add_u64 v[160:161], s[52:53], 0, v[136:137]
	s_mov_b32 m0, s78
	ds_read_b128 v[206:209], v165 offset:16384
	ds_read_b128 v[210:213], v165 offset:17408
	ds_read_b128 v[214:217], v165 offset:18432
	ds_read_b128 v[218:221], v165 offset:19456
	ds_read_b128 v[222:225], v165 offset:20480
	ds_read_b128 v[226:229], v165 offset:21504
	ds_read_b128 v[230:233], v165 offset:22528
	ds_read_b128 v[234:237], v165 offset:23552
	global_load_lds_dwordx4 v[160:161], off
	s_add_i32 m0, s78, 0x2000
	s_add_u32 vcc_lo, s52, 0x80000
	v_lshl_add_u64 v[190:191], s[52:53], 0, v[128:129]
	s_addc_u32 vcc_hi, s53, 0
	s_add_i32 s4, s4, s34
	global_load_lds_dwordx4 v[190:191], off
	v_lshl_add_u64 v[240:241], s[54:55], 0, v[130:131]
	v_lshl_add_u64 v[238:239], s[54:55], 0, v[132:133]
	s_mov_b32 m0, s36
	s_nop 0
	global_load_lds_dwordx4 v[238:239], off
	s_mov_b32 m0, s56
	s_nop 0
	global_load_lds_dwordx4 v[240:241], off
	s_waitcnt vmcnt(6)
	s_waitcnt lgkmcnt(0)
	s_barrier
; #define PG8_STAGE(bufoff, gbase, voff) do { _Pragma("unroll") for (int _i = 0; _i < 2; ++_i) \
;         __builtin_amdgcn_global_load_lds((const unsigned*)((const char*)(gbase) + (voff)[_i]), (LAS unsigned*)(lds + (bufoff) + ldsw + _i * 8192), 16, 0, PG8_AUX); } while (0)
; #define PG8_LDA(dst, b, h) do { _Pragma("unroll") for (int m = 0; m < 4; ++m) _Pragma("unroll") for (int k = 0; k < 2; ++k) dst[m][k] = *(const LAS bf16x8*)(lds + PG8_SA(b, h) + aoff + m * 2048 + k * 1024); } while (0)
; #define PG8_LDB(dst, b, h) do { _Pragma("unroll") for (int n = 0; n < 2; ++n) _Pragma("unroll") for (int k = 0; k < 2; ++k) dst[n][k] = *(const LAS bf16x8*)(lds + PG8_SB(b, h) + boff + n * 2048 + k * 1024); } while (0)
; #define PG8_MMA(ai, bj, At, Bt) do { __builtin_amdgcn_s_setprio(1); _Pragma("unroll") for (int m = 0; m < 4; ++m) _Pragma("unroll") for (int n = 0; n < 2; ++n) _Pragma("unroll") for (int k = 0; k < 2; ++k) \
;         acc[ai][bj][m][n] = __builtin_amdgcn_mfma_f32_16x16x32_bf16(Bt[n][k], At[m][k], acc[ai][bj][m][n], 0, 0, 0); __builtin_amdgcn_s_setprio(0); } while (0)
; #define PG8_WAIT_V(n) asm volatile("s_waitcnt vmcnt(" #n ")" ::: "memory")
; #define PG8_WAIT_L(n) asm volatile("s_waitcnt lgkmcnt(" #n ")" ::: "memory")
; #define PG8_BAR __builtin_amdgcn_s_barrier()
; #define PG8_SCHED __builtin_amdgcn_sched_barrier(0)
; template <class Epi, class Sched>
; __device__ __forceinline__ void gemm_phase(LAS unsigned char* lds, const Gemm g, const Sched& S, const Epi& E) {
;     ...
;             PG8_WAIT_V(8); PG8_WAIT_L(0); PG8_BAR; PG8_MMA(1, 0, At, B0); PG8_MMA(1, 1, At, B1); PG8_BAR; PG8_SCHED;
;             PG8_LDB(B0, 1, 0); PG8_LDB(B1, 1, 1); PG8_SCHED; PG8_LDA(At, 1, 0); PG8_STAGE(PG8_SA(0, 1), a2 + hstepA, voffA);
;             PG8_WAIT_V(8); PG8_WAIT_L(0); PG8_BAR; PG8_MMA(0, 0, At, B0); PG8_MMA(0, 1, At, B1); PG8_BAR; PG8_SCHED;
	s_setprio 1
	s_waitcnt lgkmcnt(0)
	v_mfma_f32_16x16x32_bf16 v[60:63], v[156:159], v[206:209], v[60:63]
	v_mfma_f32_16x16x32_bf16 v[52:55], v[170:173], v[206:209], v[52:55]
	v_mfma_f32_16x16x32_bf16 v[44:47], v[156:159], v[214:217], v[44:47]
	v_mfma_f32_16x16x32_bf16 v[36:39], v[170:173], v[214:217], v[36:39]
	v_mfma_f32_16x16x32_bf16 v[28:31], v[156:159], v[222:225], v[28:31]
	v_mfma_f32_16x16x32_bf16 v[20:23], v[170:173], v[222:225], v[20:23]
	v_mfma_f32_16x16x32_bf16 v[12:15], v[156:159], v[230:233], v[12:15]
	v_mfma_f32_16x16x32_bf16 v[4:7], v[170:173], v[230:233], v[4:7]
	v_mfma_f32_16x16x32_bf16 v[60:63], v[166:169], v[210:213], v[60:63]
	v_mfma_f32_16x16x32_bf16 v[52:55], v[182:185], v[210:213], v[52:55]
	v_mfma_f32_16x16x32_bf16 v[44:47], v[166:169], v[218:221], v[44:47]
	v_mfma_f32_16x16x32_bf16 v[36:39], v[182:185], v[218:221], v[36:39]
	v_mfma_f32_16x16x32_bf16 v[28:31], v[166:169], v[226:229], v[28:31]
	v_mfma_f32_16x16x32_bf16 v[20:23], v[182:185], v[226:229], v[20:23]
	v_mfma_f32_16x16x32_bf16 v[12:15], v[166:169], v[234:237], v[12:15]
	v_mfma_f32_16x16x32_bf16 v[4:7], v[182:185], v[234:237], v[4:7]
	s_setprio 0
	s_setprio 1
	v_mfma_f32_16x16x32_bf16 v[56:59], v[186:189], v[206:209], v[56:59]
	v_mfma_f32_16x16x32_bf16 v[48:51], v[198:201], v[206:209], v[48:51]
	v_mfma_f32_16x16x32_bf16 v[40:43], v[186:189], v[214:217], v[40:43]
	v_mfma_f32_16x16x32_bf16 v[32:35], v[198:201], v[214:217], v[32:35]
	v_mfma_f32_16x16x32_bf16 v[24:27], v[186:189], v[222:225], v[24:27]
	v_mfma_f32_16x16x32_bf16 v[16:19], v[198:201], v[222:225], v[16:19]
	v_mfma_f32_16x16x32_bf16 v[8:11], v[186:189], v[230:233], v[8:11]
	v_mfma_f32_16x16x32_bf16 v[0:3], v[198:201], v[230:233], v[0:3]
	v_mfma_f32_16x16x32_bf16 v[56:59], v[194:197], v[210:213], v[56:59]
	v_mfma_f32_16x16x32_bf16 v[48:51], v[202:205], v[210:213], v[48:51]
	v_mfma_f32_16x16x32_bf16 v[40:43], v[194:197], v[218:221], v[40:43]
	v_mfma_f32_16x16x32_bf16 v[32:35], v[202:205], v[218:221], v[32:35]
	v_mfma_f32_16x16x32_bf16 v[24:27], v[194:197], v[226:229], v[24:27]
	v_mfma_f32_16x16x32_bf16 v[16:19], v[202:205], v[226:229], v[16:19]
	v_mfma_f32_16x16x32_bf16 v[8:11], v[194:197], v[234:237], v[8:11]
	v_mfma_f32_16x16x32_bf16 v[0:3], v[202:205], v[234:237], v[0:3]
	s_setprio 0
	s_barrier
	s_add_i32 s4, 0, 0x18000
	v_add_u32_e32 v181, s4, v163
	s_add_i32 s78, 0, 0x1c000
	ds_read_b128 v[156:159], v181
	ds_read_b128 v[166:169], v181 offset:1024
	ds_read_b128 v[170:173], v181 offset:2048
	ds_read_b128 v[182:185], v181 offset:3072
	v_add_u32_e32 v181, s78, v163
	ds_read_b128 v[186:189], v181
	ds_read_b128 v[194:197], v181 offset:1024
	ds_read_b128 v[198:201], v181 offset:2048
	ds_read_b128 v[202:205], v181 offset:3072
	s_add_u32 s54, s54, 0x80000
	s_addc_u32 s55, s55, 0
	s_mov_b32 m0, s57
	v_lshl_add_u64 v[242:243], s[54:55], 0, v[132:133]
	ds_read_b128 v[206:209], v165 offset:32768
	ds_read_b128 v[210:213], v165 offset:33792
	ds_read_b128 v[214:217], v165 offset:34816
	ds_read_b128 v[218:221], v165 offset:35840
	ds_read_b128 v[222:225], v165 offset:36864
	ds_read_b128 v[226:229], v165 offset:37888
	ds_read_b128 v[230:233], v165 offset:38912
	ds_read_b128 v[234:237], v165 offset:39936
	s_add_u32 s100, s52, 0x80000
	s_addc_u32 s101, s53, 0
	s_add_i32 m0, s34, 0x14000
	s_nop 0
	global_load_lds_dwordx4 v136, s[100:101]
	s_add_i32 m0, s34, 0x16000
	s_nop 0
	global_load_lds_dwordx4 v128, s[100:101]
	s_mov_b32 m0, s57
	s_nop 0
	global_load_lds_dwordx4 v[242:243], off
	v_lshl_add_u64 v[242:243], s[54:55], 0, v[130:131]
	s_mov_b32 m0, s62
	s_nop 0
	global_load_lds_dwordx4 v[242:243], off
	s_waitcnt vmcnt(8)
	s_waitcnt lgkmcnt(0)
	s_barrier
	s_setprio 1
	s_waitcnt lgkmcnt(0)
	v_mfma_f32_16x16x32_bf16 v[124:127], v[156:159], v[206:209], v[124:127]
	v_mfma_f32_16x16x32_bf16 v[116:119], v[170:173], v[206:209], v[116:119]
	v_mfma_f32_16x16x32_bf16 v[108:111], v[156:159], v[214:217], v[108:111]
	v_mfma_f32_16x16x32_bf16 v[100:103], v[170:173], v[214:217], v[100:103]
	v_mfma_f32_16x16x32_bf16 v[92:95], v[156:159], v[222:225], v[92:95]
	v_mfma_f32_16x16x32_bf16 v[84:87], v[170:173], v[222:225], v[84:87]
	v_mfma_f32_16x16x32_bf16 v[76:79], v[156:159], v[230:233], v[76:79]
	v_mfma_f32_16x16x32_bf16 v[68:71], v[170:173], v[230:233], v[68:71]
	v_mfma_f32_16x16x32_bf16 v[124:127], v[166:169], v[210:213], v[124:127]
	v_mfma_f32_16x16x32_bf16 v[116:119], v[182:185], v[210:213], v[116:119]
	v_mfma_f32_16x16x32_bf16 v[108:111], v[166:169], v[218:221], v[108:111]
	v_mfma_f32_16x16x32_bf16 v[100:103], v[182:185], v[218:221], v[100:103]
	v_mfma_f32_16x16x32_bf16 v[92:95], v[166:169], v[226:229], v[92:95]
	v_mfma_f32_16x16x32_bf16 v[84:87], v[182:185], v[226:229], v[84:87]
	v_mfma_f32_16x16x32_bf16 v[76:79], v[166:169], v[234:237], v[76:79]
	v_mfma_f32_16x16x32_bf16 v[68:71], v[182:185], v[234:237], v[68:71]
	s_setprio 0
	s_setprio 1
	v_mfma_f32_16x16x32_bf16 v[120:123], v[186:189], v[206:209], v[120:123]
	v_mfma_f32_16x16x32_bf16 v[112:115], v[198:201], v[206:209], v[112:115]
	v_mfma_f32_16x16x32_bf16 v[104:107], v[186:189], v[214:217], v[104:107]
	v_mfma_f32_16x16x32_bf16 v[96:99], v[198:201], v[214:217], v[96:99]
	v_mfma_f32_16x16x32_bf16 v[88:91], v[186:189], v[222:225], v[88:91]
	v_mfma_f32_16x16x32_bf16 v[80:83], v[198:201], v[222:225], v[80:83]
	v_mfma_f32_16x16x32_bf16 v[72:75], v[186:189], v[230:233], v[72:75]
	v_mfma_f32_16x16x32_bf16 v[64:67], v[198:201], v[230:233], v[64:67]
	v_mfma_f32_16x16x32_bf16 v[120:123], v[194:197], v[210:213], v[120:123]
	v_mfma_f32_16x16x32_bf16 v[112:115], v[202:205], v[210:213], v[112:115]
	v_mfma_f32_16x16x32_bf16 v[104:107], v[194:197], v[218:221], v[104:107]
	v_mfma_f32_16x16x32_bf16 v[96:99], v[202:205], v[218:221], v[96:99]
	v_mfma_f32_16x16x32_bf16 v[88:91], v[194:197], v[226:229], v[88:91]
	v_mfma_f32_16x16x32_bf16 v[80:83], v[202:205], v[226:229], v[80:83]
	v_mfma_f32_16x16x32_bf16 v[72:75], v[194:197], v[234:237], v[72:75]
	v_mfma_f32_16x16x32_bf16 v[64:67], v[202:205], v[234:237], v[64:67]
	s_setprio 0
	s_barrier
; #define PG8_STAGE(bufoff, gbase, voff) do { _Pragma("unroll") for (int _i = 0; _i < 2; ++_i) \
;         __builtin_amdgcn_global_load_lds((const unsigned*)((const char*)(gbase) + (voff)[_i]), (LAS unsigned*)(lds + (bufoff) + ldsw + _i * 8192), 16, 0, PG8_AUX); } while (0)
; #define PG8_LDA(dst, b, h) do { _Pragma("unroll") for (int m = 0; m < 4; ++m) _Pragma("unroll") for (int k = 0; k < 2; ++k) dst[m][k] = *(const LAS bf16x8*)(lds + PG8_SA(b, h) + aoff + m * 2048 + k * 1024); } while (0)
; #define PG8_WAIT_V(n) asm volatile("s_waitcnt vmcnt(" #n ")" ::: "memory")
; #define PG8_WAIT_L(n) asm volatile("s_waitcnt lgkmcnt(" #n ")" ::: "memory")
; template <class Epi, class Sched>
; __device__ __forceinline__ void gemm_phase(LAS unsigned char* lds, const Gemm g, const Sched& S, const Epi& E) {
;     ...
;             PG8_LDA(At, 1, 1); PG8_STAGE(PG8_SB(1, 0), b3, voffB); PG8_STAGE(PG8_SB(1, 1), b3 + hstepB, voffB); PG8_STAGE(PG8_SA(1, 0), a3, voffA);
;             PG8_WAIT_V(8); PG8_WAIT_L(0); PG8_BAR; PG8_MMA(1, 0, At, B0); PG8_MMA(1, 1, At, B1); PG8_BAR; PG8_SCHED;
;     ...
;             PG8_LDB(B0, 0, 0); PG8_SCHED; PG8_LDA(At, 0, 0); PG8_STAGE(PG8_SA(1, 1), a1 + hstepA, voffA);
;             PG8_WAIT_L(8); PG8_BAR; PG8_WAIT_L(0); PG8_MMA(0, 0, At, B0); PG8_BAR; PG8_SCHED;
;             PG8_LDB(B1, 0, 1); PG8_STAGE(PG8_SB(0, 0), b2, voffB);
;             PG8_BAR; PG8_WAIT_L(0); PG8_MMA(0, 1, At, B1); PG8_BAR;
;             PG8_LDA(At, 0, 1); PG8_STAGE(PG8_SA(0, 0), a2, voffA);
;             PG8_BAR; PG8_WAIT_L(0); PG8_MMA(1, 0, At, B0); PG8_BAR; PG8_SCHED;
;             PG8_STAGE(PG8_SB(0, 1), b2 + hstepB, voffB);
;             PG8_WAIT_V(6); PG8_BAR; PG8_MMA(1, 1, At, B1); PG8_BAR;
;             PG8_LDB(B0, 1, 0); PG8_SCHED; PG8_LDA(At, 1, 0); PG8_STAGE(PG8_SA(0, 1), a2 + hstepA, voffA);
;             PG8_WAIT_L(8); PG8_BAR; PG8_WAIT_L(0); PG8_MMA(0, 0, At, B0); PG8_BAR; PG8_SCHED;
;             PG8_LDB(B1, 1, 1); PG8_STAGE(PG8_SB(1, 0), b3, voffB);
;             PG8_BAR; PG8_WAIT_L(0); PG8_MMA(0, 1, At, B1); PG8_BAR;
;             PG8_LDA(At, 1, 1); PG8_STAGE(PG8_SA(1, 0), a3, voffA);
;             PG8_BAR; PG8_WAIT_L(0); PG8_MMA(1, 0, At, B0); PG8_BAR; PG8_SCHED;
;             PG8_STAGE(PG8_SB(1, 1), b3 + hstepB, voffB);
;             PG8_WAIT_V(6); PG8_BAR; PG8_MMA(1, 1, At, B1); PG8_BAR;
;     ...
;         }
;     ...
;         if (wr == 0) PG8_BAR;
	s_add_i32 s4, s4, s34
	v_lshl_add_u64 v[160:161], v[160:161], 0, s[12:13]
	s_mov_b32 m0, s4
	ds_read_b128 v[206:209], v165 offset:49152
	ds_read_b128 v[210:213], v165 offset:50176
	ds_read_b128 v[214:217], v165 offset:51200
	ds_read_b128 v[218:221], v165 offset:52224
	ds_read_b128 v[222:225], v165 offset:53248
	ds_read_b128 v[226:229], v165 offset:54272
	ds_read_b128 v[230:233], v165 offset:55296
	ds_read_b128 v[234:237], v165 offset:56320
	global_load_lds_dwordx4 v[160:161], off
	s_add_i32 m0, s4, 0x2000
	s_add_u32 s52, s52, 0x80080
	v_lshl_add_u64 v[160:161], v[190:191], 0, s[12:13]
	s_addc_u32 s53, s53, 0
	s_add_i32 s4, s78, s34
	global_load_lds_dwordx4 v[160:161], off
	v_lshl_add_u64 v[160:161], s[52:53], 0, v[136:137]
	s_mov_b32 m0, s4
	s_nop 0
	global_load_lds_dwordx4 v[160:161], off
	v_lshl_add_u64 v[160:161], s[52:53], 0, v[128:129]
	s_add_i32 m0, s4, 0x2000
	s_nop 0
	global_load_lds_dwordx4 v[160:161], off
	v_lshl_add_u64 v[160:161], v[238:239], 0, s[12:13]
	s_mov_b32 m0, s63
	s_nop 0
	global_load_lds_dwordx4 v[160:161], off
	v_lshl_add_u64 v[160:161], v[240:241], 0, s[12:13]
	s_mov_b32 m0, s64
	s_nop 0
	global_load_lds_dwordx4 v[160:161], off
	s_waitcnt vmcnt(8)
	s_waitcnt lgkmcnt(0)
	s_barrier
	s_setprio 1
	s_waitcnt lgkmcnt(0)
	v_mfma_f32_16x16x32_bf16 v[60:63], v[156:159], v[206:209], v[60:63]
	v_mfma_f32_16x16x32_bf16 v[52:55], v[170:173], v[206:209], v[52:55]
	v_mfma_f32_16x16x32_bf16 v[44:47], v[156:159], v[214:217], v[44:47]
	v_mfma_f32_16x16x32_bf16 v[36:39], v[170:173], v[214:217], v[36:39]
	v_mfma_f32_16x16x32_bf16 v[28:31], v[156:159], v[222:225], v[28:31]
	v_mfma_f32_16x16x32_bf16 v[20:23], v[170:173], v[222:225], v[20:23]
	v_mfma_f32_16x16x32_bf16 v[12:15], v[156:159], v[230:233], v[12:15]
	v_mfma_f32_16x16x32_bf16 v[4:7], v[170:173], v[230:233], v[4:7]
	v_mfma_f32_16x16x32_bf16 v[60:63], v[166:169], v[210:213], v[60:63]
	v_mfma_f32_16x16x32_bf16 v[52:55], v[182:185], v[210:213], v[52:55]
	v_mfma_f32_16x16x32_bf16 v[44:47], v[166:169], v[218:221], v[44:47]
	v_mfma_f32_16x16x32_bf16 v[36:39], v[182:185], v[218:221], v[36:39]
	v_mfma_f32_16x16x32_bf16 v[28:31], v[166:169], v[226:229], v[28:31]
	v_mfma_f32_16x16x32_bf16 v[20:23], v[182:185], v[226:229], v[20:23]
	v_mfma_f32_16x16x32_bf16 v[12:15], v[166:169], v[234:237], v[12:15]
	v_mfma_f32_16x16x32_bf16 v[4:7], v[182:185], v[234:237], v[4:7]
	s_setprio 0
	s_setprio 1
	v_mfma_f32_16x16x32_bf16 v[56:59], v[186:189], v[206:209], v[56:59]
	v_mfma_f32_16x16x32_bf16 v[48:51], v[198:201], v[206:209], v[48:51]
	v_mfma_f32_16x16x32_bf16 v[40:43], v[186:189], v[214:217], v[40:43]
	v_mfma_f32_16x16x32_bf16 v[32:35], v[198:201], v[214:217], v[32:35]
	v_mfma_f32_16x16x32_bf16 v[24:27], v[186:189], v[222:225], v[24:27]
	v_mfma_f32_16x16x32_bf16 v[16:19], v[198:201], v[222:225], v[16:19]
	v_mfma_f32_16x16x32_bf16 v[8:11], v[186:189], v[230:233], v[8:11]
	v_mfma_f32_16x16x32_bf16 v[0:3], v[198:201], v[230:233], v[0:3]
	v_mfma_f32_16x16x32_bf16 v[56:59], v[194:197], v[210:213], v[56:59]
	v_mfma_f32_16x16x32_bf16 v[48:51], v[202:205], v[210:213], v[48:51]
	v_mfma_f32_16x16x32_bf16 v[40:43], v[194:197], v[218:221], v[40:43]
	v_mfma_f32_16x16x32_bf16 v[32:35], v[202:205], v[218:221], v[32:35]
	v_mfma_f32_16x16x32_bf16 v[24:27], v[194:197], v[226:229], v[24:27]
	v_mfma_f32_16x16x32_bf16 v[16:19], v[202:205], v[226:229], v[16:19]
	v_mfma_f32_16x16x32_bf16 v[8:11], v[194:197], v[234:237], v[8:11]
	v_mfma_f32_16x16x32_bf16 v[0:3], v[202:205], v[234:237], v[0:3]
	s_setprio 0
	s_barrier
	s_add_i32 s94, s94, 2
	s_add_u32 s22, s22, 0x100
	s_addc_u32 s23, s23, 0
	s_add_u32 s65, s65, 0x100
	s_addc_u32 s92, s92, 0
	s_cmp_gt_u32 s94, 29
	s_cbranch_scc0 .LBB0_745
	s_and_b64 vcc, exec, s[42:43]
	s_cbranch_vccz .LBB0_748
	s_barrier

; __global__ void __launch_bounds__(512, 2) mega_fwd(Args a) {
;     extern __shared__ __attribute__((aligned(16))) unsigned char lds[];
	.amdhsa_kernel _Z8mega_fwd4Args
		.amdhsa_group_segment_fixed_size 0
		.amdhsa_private_segment_fixed_size 0
		.amdhsa_kernarg_size 504
		.amdhsa_user_sgpr_count 2
		.amdhsa_user_sgpr_dispatch_ptr 0
		.amdhsa_user_sgpr_queue_ptr 0
		.amdhsa_user_sgpr_kernarg_segment_ptr 1
		.amdhsa_user_sgpr_dispatch_id 0
		.amdhsa_user_sgpr_kernarg_preload_length 0
		.amdhsa_user_sgpr_kernarg_preload_offset 0
		.amdhsa_user_sgpr_private_segment_size 0
		.amdhsa_uses_dynamic_stack 0
		.amdhsa_enable_private_segment 0
		.amdhsa_system_sgpr_workgroup_id_x 1
		.amdhsa_system_sgpr_workgroup_id_y 0
		.amdhsa_system_sgpr_workgroup_id_z 0
		.amdhsa_system_sgpr_workgroup_info 0
		.amdhsa_system_vgpr_workitem_id 2
		.amdhsa_next_free_vgpr 255
		.amdhsa_next_free_sgpr 102
		.amdhsa_accum_offset 256
		.amdhsa_reserve_vcc 1
		.amdhsa_float_round_mode_32 0
		.amdhsa_float_round_mode_16_64 0
		.amdhsa_float_denorm_mode_32 3
		.amdhsa_float_denorm_mode_16_64 3
		.amdhsa_dx10_clamp 1
		.amdhsa_ieee_mode 1
		.amdhsa_fp16_overflow 0
		.amdhsa_tg_split 0
		.amdhsa_exception_fp_ieee_invalid_op 0
		.amdhsa_exception_fp_denorm_src 0
		.amdhsa_exception_fp_ieee_div_zero 0
		.amdhsa_exception_fp_ieee_overflow 0
		.amdhsa_exception_fp_ieee_underflow 0
		.amdhsa_exception_fp_ieee_inexact 0
		.amdhsa_exception_int_div_zero 0
	.end_amdhsa_kernel

; __global__ void __launch_bounds__(512, 2) mega_fwd(Args a) {
;     extern __shared__ __attribute__((aligned(16))) unsigned char lds[];
amdhsa.kernels:
  - .agpr_count:     0
    .args:
      - .offset:         0
        .size:           248
        .value_kind:     by_value
      - .offset:         248
        .size:           4
        .value_kind:     hidden_block_count_x
      - .offset:         252
        .size:           4
        .value_kind:     hidden_block_count_y
      - .offset:         256
        .size:           4
        .value_kind:     hidden_block_count_z
      - .offset:         260
        .size:           2
        .value_kind:     hidden_group_size_x
      - .offset:         262
        .size:           2
        .value_kind:     hidden_group_size_y
      - .offset:         264
        .size:           2
        .value_kind:     hidden_group_size_z
      - .offset:         266
        .size:           2
        .value_kind:     hidden_remainder_x
      - .offset:         268
        .size:           2
        .value_kind:     hidden_remainder_y
      - .offset:         270
        .size:           2
        .value_kind:     hidden_remainder_z
      - .offset:         288
        .size:           8
        .value_kind:     hidden_global_offset_x
      - .offset:         296
        .size:           8
        .value_kind:     hidden_global_offset_y
      - .offset:         304
        .size:           8
        .value_kind:     hidden_global_offset_z
      - .offset:         312
        .size:           2
        .value_kind:     hidden_grid_dims
      - .offset:         336
        .size:           8
        .value_kind:     hidden_multigrid_sync_arg
      - .offset:         368
        .size:           4
        .value_kind:     hidden_dynamic_lds_size
    .group_segment_fixed_size: 0
    .kernarg_segment_align: 8
    .kernarg_segment_size: 504
    .language:       OpenCL C
    .language_version:
      - 2
      - 0
    .max_flat_workgroup_size: 512
    .name:           _Z8mega_fwd4Args
    .private_segment_fixed_size: 0
    .sgpr_count:     108
    .sgpr_spill_count: 460
    .symbol:         _Z8mega_fwd4Args.kd
    .uniform_work_group_size: 1
    .uses_dynamic_stack: false
    .vgpr_count:     255
    .vgpr_spill_count: 0
    .wavefront_size: 64
